# attention branch end: gate scalars loaded before the tile loop, counted vmcnt(4) instead of a full drain
# baseline (speedup 1.0000x reference)
.LBB0_1102:
	s_waitcnt vmcnt(0)
	v_pk_mul_f32 v[0:1], v[66:67], v[0:1] op_sel_hi:[0,1]
	v_cvt_pk_bf16_f32 v177, v0, v1
	v_pk_mul_f32 v[0:1], v[66:67], v[2:3] op_sel_hi:[0,1]
	v_cvt_pk_bf16_f32 v176, v0, v1
	v_pk_mul_f32 v[0:1], v[66:67], v[4:5] op_sel_hi:[0,1]
	v_cvt_pk_bf16_f32 v175, v0, v1
	v_pk_mul_f32 v[0:1], v[66:67], v[6:7] op_sel_hi:[0,1]
	v_cvt_pk_bf16_f32 v174, v0, v1
	v_pk_mul_f32 v[0:1], v[66:67], v[8:9] op_sel_hi:[0,1]
	v_cvt_pk_bf16_f32 v173, v0, v1
	v_pk_mul_f32 v[0:1], v[66:67], v[10:11] op_sel_hi:[0,1]
	v_pk_mul_f32 v[50:51], v[50:51], v[66:67] op_sel_hi:[1,0]
	v_pk_mul_f32 v[34:35], v[34:35], v[66:67] op_sel_hi:[1,0]
	v_pk_mul_f32 v[16:17], v[16:17], v[66:67] op_sel_hi:[1,0]
	v_cvt_pk_bf16_f32 v172, v0, v1
	v_pk_mul_f32 v[0:1], v[66:67], v[12:13] op_sel_hi:[0,1]
	v_cvt_pk_bf16_f32 v203, v50, v51
	v_pk_mul_f32 v[50:51], v[52:53], v[66:67] op_sel_hi:[1,0]
	v_cvt_pk_bf16_f32 v195, v34, v35
	v_pk_mul_f32 v[34:35], v[36:37], v[66:67] op_sel_hi:[1,0]
	v_cvt_pk_bf16_f32 v187, v16, v17
	v_pk_mul_f32 v[16:17], v[18:19], v[66:67] op_sel_hi:[1,0]
	v_cvt_pk_bf16_f32 v171, v0, v1
	v_pk_mul_f32 v[0:1], v[66:67], v[14:15] op_sel_hi:[0,1]
	v_cvt_pk_bf16_f32 v202, v50, v51
	v_pk_mul_f32 v[50:51], v[54:55], v[66:67] op_sel_hi:[1,0]
	v_cvt_pk_bf16_f32 v194, v34, v35
	v_pk_mul_f32 v[34:35], v[38:39], v[66:67] op_sel_hi:[1,0]
	v_cvt_pk_bf16_f32 v186, v16, v17
	v_pk_mul_f32 v[16:17], v[20:21], v[66:67] op_sel_hi:[1,0]
	v_cvt_pk_bf16_f32 v170, v0, v1
	s_waitcnt vmcnt(0) lgkmcnt(0)
	s_barrier
	v_mov_b32_e32 v1, s45
	s_lshl_b32 s14, s92, 18
	v_cvt_pk_bf16_f32 v201, v50, v51
	v_pk_mul_f32 v[50:51], v[56:57], v[66:67] op_sel_hi:[1,0]
	v_cvt_pk_bf16_f32 v193, v34, v35
	v_pk_mul_f32 v[34:35], v[40:41], v[66:67] op_sel_hi:[1,0]
	v_cvt_pk_bf16_f32 v185, v16, v17
	v_pk_mul_f32 v[16:17], v[22:23], v[66:67] op_sel_hi:[1,0]
	ds_read_b32 v1, v1
	s_mov_b64 s[2:3], 0x11341000
	v_cvt_pk_bf16_f32 v200, v50, v51
	v_pk_mul_f32 v[50:51], v[58:59], v[66:67] op_sel_hi:[1,0]
	v_cvt_pk_bf16_f32 v192, v34, v35
	v_pk_mul_f32 v[34:35], v[42:43], v[66:67] op_sel_hi:[1,0]
	v_cvt_pk_bf16_f32 v184, v16, v17
	v_pk_mul_f32 v[16:17], v[24:25], v[66:67] op_sel_hi:[1,0]
	s_add_u32 s15, s80, 0x31e51000
	v_lshl_add_u32 v0, v126, 2, 0
	v_mov_b32_e32 v2, s86
	v_lshl_add_u64 v[162:163], v[68:69], 0, s[2:3]
	global_load_dword v228, v[162:163], off offset:64
	global_load_dword v229, v[162:163], off offset:128
	v_cvt_pk_bf16_f32 v199, v50, v51
	v_pk_mul_f32 v[50:51], v[60:61], v[66:67] op_sel_hi:[1,0]
	v_cvt_pk_bf16_f32 v191, v34, v35
	v_pk_mul_f32 v[34:35], v[44:45], v[66:67] op_sel_hi:[1,0]
	v_cvt_pk_bf16_f32 v183, v16, v17
	v_pk_mul_f32 v[16:17], v[26:27], v[66:67] op_sel_hi:[1,0]
	s_addc_u32 s16, s81, 0
	v_add_u32_e32 v0, 0x1ad00, v0
	ds_read_b32 v204, v2 offset:508
	ds_read_b32 v205, v0
	s_lshl_b32 s3, 2, s79
	v_cvt_pk_bf16_f32 v198, v50, v51
	v_pk_mul_f32 v[50:51], v[62:63], v[66:67] op_sel_hi:[1,0]
	v_cvt_pk_bf16_f32 v190, v34, v35
	v_pk_mul_f32 v[34:35], v[46:47], v[66:67] op_sel_hi:[1,0]
	v_cvt_pk_bf16_f32 v182, v16, v17
	v_pk_mul_f32 v[16:17], v[28:29], v[66:67] op_sel_hi:[1,0]
	s_add_i32 s3, s3, -1
	v_cvt_pk_bf16_f32 v197, v50, v51
	v_pk_mul_f32 v[50:51], v[64:65], v[66:67] op_sel_hi:[1,0]
	v_cvt_pk_bf16_f32 v189, v34, v35
	v_pk_mul_f32 v[34:35], v[48:49], v[66:67] op_sel_hi:[1,0]
	v_cvt_pk_bf16_f32 v181, v16, v17
	v_pk_mul_f32 v[16:17], v[30:31], v[66:67] op_sel_hi:[1,0]
	s_cmp_gt_u32 s93, 31
	v_mov_b32_e32 v66, v33
	v_mov_b32_e32 v67, v33
	v_mov_b32_e32 v80, v33
	v_mov_b32_e32 v81, v33
	v_cvt_pk_bf16_f32 v196, v50, v51
	v_cvt_pk_bf16_f32 v188, v34, v35
	s_waitcnt lgkmcnt(0)
	v_readfirstlane_b32 s2, v1
	s_cselect_b32 s3, s3, -2
	v_sub_u32_e64 v0, s79, 8 clamp
	v_mov_b32_e32 v68, v33
	v_mov_b32_e32 v69, v33
	v_mov_b32_e32 v70, v33
	v_mov_b32_e32 v71, v33
	v_mov_b32_e32 v72, v33
	v_mov_b32_e32 v73, v33
	v_mov_b32_e32 v74, v33
	v_mov_b32_e32 v75, v33
	v_mov_b32_e32 v76, v33
	v_mov_b32_e32 v77, v33
	v_mov_b32_e32 v78, v33
	v_mov_b32_e32 v79, v33
	v_mov_b64_e32 v[96:97], v[80:81]
	v_mov_b64_e32 v[50:51], v[66:67]
	v_mov_b64_e32 v[34:35], v[66:67]
	v_cvt_pk_bf16_f32 v180, v16, v17
	s_add_i32 s17, s96, 0xffffff41
	v_lshl_add_u32 v206, v124, 10, v127
	s_and_b32 s18, s2, s3
	v_readfirstlane_b32 s19, v0
	s_or_b32 s20, s96, 63
	v_sub_u32_e32 v207, v125, v128
	s_mov_b32 s21, 0
	s_mov_b32 s23, 1
	v_mov_b32_e32 v208, 0
	v_mov_b32_e32 v209, 0xc69c4000
	v_lshlrev_b64 v[164:165], 1, v[32:33]
	v_mov_b64_e32 v[94:95], v[78:79]
	v_mov_b64_e32 v[92:93], v[76:77]
	v_mov_b64_e32 v[90:91], v[74:75]
	v_mov_b64_e32 v[88:89], v[72:73]
	v_mov_b64_e32 v[86:87], v[70:71]
	v_mov_b64_e32 v[84:85], v[68:69]
	v_mov_b64_e32 v[82:83], v[66:67]
	v_mov_b64_e32 v[52:53], v[68:69]
	v_mov_b64_e32 v[54:55], v[70:71]
	v_mov_b64_e32 v[56:57], v[72:73]
	v_mov_b64_e32 v[58:59], v[74:75]
	v_mov_b64_e32 v[60:61], v[76:77]
	v_mov_b64_e32 v[62:63], v[78:79]
	v_mov_b64_e32 v[64:65], v[80:81]
	v_mov_b64_e32 v[36:37], v[68:69]
	v_mov_b64_e32 v[38:39], v[70:71]
	v_mov_b64_e32 v[40:41], v[72:73]
	v_mov_b64_e32 v[42:43], v[74:75]
	v_mov_b64_e32 v[44:45], v[76:77]
	v_mov_b64_e32 v[46:47], v[78:79]
	v_mov_b64_e32 v[48:49], v[80:81]
	s_mov_b32 s10, 0

.LBB0_1113:
	s_and_b64 s[2:3], exec, s[8:9]
	s_cselect_b32 s60, 0x80, 64
	s_waitcnt vmcnt(4)
	v_cndmask_b32_e64 v32, v228, v229, s[2:3]
	ds_bpermute_b32 v31, v168, v208
	v_lshlrev_b32_e32 v0, 16, v203
	v_and_b32_e32 v1, 0xffff0000, v203
	v_lshlrev_b32_e32 v2, 16, v202
	v_and_b32_e32 v3, 0xffff0000, v202
	s_waitcnt lgkmcnt(0)
	v_add_f32_e32 v98, v208, v31
	v_div_scale_f32 v99, s[2:3], v98, v98, 1.0
	v_rcp_f32_e32 v100, v99
	v_div_scale_f32 v101, vcc, 1.0, v98, 1.0
	v_lshlrev_b32_e32 v4, 16, v201
	v_fma_f32 v102, -v99, v100, 1.0
	v_fmac_f32_e32 v100, v102, v100
	v_mul_f32_e32 v102, v101, v100
	v_fma_f32 v103, -v99, v102, v101
	v_fmac_f32_e32 v102, v103, v100
	v_fma_f32 v99, -v99, v102, v101
	v_div_fmas_f32 v99, v99, v100, v102
	v_div_fixup_f32 v99, v99, v98, 1.0
	v_cmp_lt_f32_e32 vcc, 0, v98
	v_and_b32_e32 v5, 0xffff0000, v201
	v_lshlrev_b32_e32 v6, 16, v200
	v_cndmask_b32_e32 v98, 0, v99, vcc
	v_and_b32_e32 v7, 0xffff0000, v200
	v_lshlrev_b32_e32 v8, 16, v199
	v_and_b32_e32 v9, 0xffff0000, v199
	v_lshlrev_b32_e32 v10, 16, v198
	v_and_b32_e32 v11, 0xffff0000, v198
	v_lshlrev_b32_e32 v12, 16, v197
	v_and_b32_e32 v13, 0xffff0000, v197
	v_lshlrev_b32_e32 v14, 16, v196
	v_and_b32_e32 v15, 0xffff0000, v196
	v_lshlrev_b32_e32 v16, 16, v195
	v_and_b32_e32 v17, 0xffff0000, v195
	v_lshlrev_b32_e32 v18, 16, v194
	v_and_b32_e32 v19, 0xffff0000, v194
	v_lshlrev_b32_e32 v20, 16, v193
	v_and_b32_e32 v21, 0xffff0000, v193
	v_lshlrev_b32_e32 v22, 16, v192
	v_and_b32_e32 v23, 0xffff0000, v192
	v_lshlrev_b32_e32 v24, 16, v191
	v_and_b32_e32 v25, 0xffff0000, v191
	v_lshlrev_b32_e32 v26, 16, v190
	v_and_b32_e32 v27, 0xffff0000, v190
	v_lshlrev_b32_e32 v28, 16, v189
	v_and_b32_e32 v29, 0xffff0000, v189
	v_lshlrev_b32_e32 v30, 16, v188
	v_and_b32_e32 v31, 0xffff0000, v188
	v_mov_b32_e32 v209, 0xc69c4000
	v_mov_b32_e32 v208, 0
	v_mul_f32_e32 v32, v32, v98
	v_pk_fma_f32 v[0:1], v[66:67], v[32:33], v[0:1] op_sel_hi:[1,0,1]
	v_pk_fma_f32 v[2:3], v[68:69], v[32:33], v[2:3] op_sel_hi:[1,0,1]
	v_cvt_pk_bf16_f32 v203, v0, v1
	v_lshlrev_b32_e32 v0, 16, v187
	v_and_b32_e32 v1, 0xffff0000, v187
	v_pk_fma_f32 v[0:1], v[50:51], v[32:33], v[0:1] op_sel_hi:[1,0,1]
	v_pk_fma_f32 v[4:5], v[70:71], v[32:33], v[4:5] op_sel_hi:[1,0,1]
	v_cvt_pk_bf16_f32 v187, v0, v1
	v_lshlrev_b32_e32 v0, 16, v186
	v_and_b32_e32 v1, 0xffff0000, v186
	v_pk_fma_f32 v[0:1], v[52:53], v[32:33], v[0:1] op_sel_hi:[1,0,1]
	v_pk_fma_f32 v[6:7], v[72:73], v[32:33], v[6:7] op_sel_hi:[1,0,1]
	v_cvt_pk_bf16_f32 v186, v0, v1
	v_lshlrev_b32_e32 v0, 16, v185
	v_and_b32_e32 v1, 0xffff0000, v185
	v_pk_fma_f32 v[0:1], v[54:55], v[32:33], v[0:1] op_sel_hi:[1,0,1]
	v_pk_fma_f32 v[8:9], v[74:75], v[32:33], v[8:9] op_sel_hi:[1,0,1]
	v_cvt_pk_bf16_f32 v185, v0, v1
	v_lshlrev_b32_e32 v0, 16, v184
	v_and_b32_e32 v1, 0xffff0000, v184
	v_pk_fma_f32 v[0:1], v[56:57], v[32:33], v[0:1] op_sel_hi:[1,0,1]
	v_pk_fma_f32 v[10:11], v[76:77], v[32:33], v[10:11] op_sel_hi:[1,0,1]
	v_cvt_pk_bf16_f32 v184, v0, v1
	v_lshlrev_b32_e32 v0, 16, v183
	v_and_b32_e32 v1, 0xffff0000, v183
	v_pk_fma_f32 v[0:1], v[58:59], v[32:33], v[0:1] op_sel_hi:[1,0,1]
	v_pk_fma_f32 v[12:13], v[78:79], v[32:33], v[12:13] op_sel_hi:[1,0,1]
	v_cvt_pk_bf16_f32 v183, v0, v1
	v_lshlrev_b32_e32 v0, 16, v182
	v_and_b32_e32 v1, 0xffff0000, v182
	v_pk_fma_f32 v[0:1], v[60:61], v[32:33], v[0:1] op_sel_hi:[1,0,1]
	v_pk_fma_f32 v[14:15], v[80:81], v[32:33], v[14:15] op_sel_hi:[1,0,1]
	v_cvt_pk_bf16_f32 v182, v0, v1
	v_lshlrev_b32_e32 v0, 16, v181
	v_and_b32_e32 v1, 0xffff0000, v181
	v_pk_fma_f32 v[0:1], v[62:63], v[32:33], v[0:1] op_sel_hi:[1,0,1]
	v_pk_fma_f32 v[16:17], v[82:83], v[32:33], v[16:17] op_sel_hi:[1,0,1]
	v_cvt_pk_bf16_f32 v181, v0, v1
	v_lshlrev_b32_e32 v0, 16, v180
	v_and_b32_e32 v1, 0xffff0000, v180
	v_pk_fma_f32 v[0:1], v[64:65], v[32:33], v[0:1] op_sel_hi:[1,0,1]
	v_pk_fma_f32 v[18:19], v[84:85], v[32:33], v[18:19] op_sel_hi:[1,0,1]
	v_cvt_pk_bf16_f32 v180, v0, v1
	v_lshlrev_b32_e32 v0, 16, v177
	v_and_b32_e32 v1, 0xffff0000, v177
	v_pk_fma_f32 v[0:1], v[34:35], v[32:33], v[0:1] op_sel_hi:[1,0,1]
	v_pk_fma_f32 v[20:21], v[86:87], v[32:33], v[20:21] op_sel_hi:[1,0,1]
	v_cvt_pk_bf16_f32 v177, v0, v1
	v_lshlrev_b32_e32 v0, 16, v176
	v_and_b32_e32 v1, 0xffff0000, v176
	v_pk_fma_f32 v[0:1], v[36:37], v[32:33], v[0:1] op_sel_hi:[1,0,1]
	v_pk_fma_f32 v[22:23], v[88:89], v[32:33], v[22:23] op_sel_hi:[1,0,1]
	v_cvt_pk_bf16_f32 v176, v0, v1
	v_lshlrev_b32_e32 v0, 16, v175
	v_and_b32_e32 v1, 0xffff0000, v175
	v_pk_fma_f32 v[0:1], v[38:39], v[32:33], v[0:1] op_sel_hi:[1,0,1]
	v_pk_fma_f32 v[24:25], v[90:91], v[32:33], v[24:25] op_sel_hi:[1,0,1]
	v_cvt_pk_bf16_f32 v175, v0, v1
	v_lshlrev_b32_e32 v0, 16, v174
	v_and_b32_e32 v1, 0xffff0000, v174
	v_pk_fma_f32 v[0:1], v[40:41], v[32:33], v[0:1] op_sel_hi:[1,0,1]
	v_pk_fma_f32 v[26:27], v[92:93], v[32:33], v[26:27] op_sel_hi:[1,0,1]
	v_cvt_pk_bf16_f32 v174, v0, v1
	v_lshlrev_b32_e32 v0, 16, v173
	v_and_b32_e32 v1, 0xffff0000, v173
	v_pk_fma_f32 v[0:1], v[42:43], v[32:33], v[0:1] op_sel_hi:[1,0,1]
	v_pk_fma_f32 v[28:29], v[94:95], v[32:33], v[28:29] op_sel_hi:[1,0,1]
	v_cvt_pk_bf16_f32 v173, v0, v1
	v_lshlrev_b32_e32 v0, 16, v172
	v_and_b32_e32 v1, 0xffff0000, v172
	v_pk_fma_f32 v[0:1], v[44:45], v[32:33], v[0:1] op_sel_hi:[1,0,1]
	v_pk_fma_f32 v[30:31], v[96:97], v[32:33], v[30:31] op_sel_hi:[1,0,1]
	v_cvt_pk_bf16_f32 v172, v0, v1
	v_lshlrev_b32_e32 v0, 16, v171
	v_and_b32_e32 v1, 0xffff0000, v171
	v_pk_fma_f32 v[0:1], v[46:47], v[32:33], v[0:1] op_sel_hi:[1,0,1]
	v_mov_b32_e32 v46, v33
	v_cvt_pk_bf16_f32 v171, v0, v1
	v_lshlrev_b32_e32 v0, 16, v170
	v_and_b32_e32 v1, 0xffff0000, v170
	v_mov_b32_e32 v47, v33
	v_pk_fma_f32 v[0:1], v[48:49], v[32:33], v[0:1] op_sel_hi:[1,0,1]
	v_mov_b32_e32 v32, v33
	v_mov_b32_e32 v34, v33
	v_mov_b32_e32 v35, v33
	v_mov_b32_e32 v36, v33
	v_mov_b32_e32 v37, v33
	v_mov_b32_e32 v38, v33
	v_mov_b32_e32 v39, v33
	v_mov_b32_e32 v40, v33
	v_mov_b32_e32 v41, v33
	v_mov_b32_e32 v42, v33
	v_mov_b32_e32 v43, v33
	v_mov_b32_e32 v44, v33
	v_mov_b32_e32 v45, v33
	v_mov_b64_e32 v[80:81], v[46:47]
	v_mov_b64_e32 v[96:97], v[46:47]
	v_mov_b64_e32 v[64:65], v[46:47]
	v_mov_b64_e32 v[78:79], v[44:45]
	v_mov_b64_e32 v[76:77], v[42:43]
	v_mov_b64_e32 v[74:75], v[40:41]
	v_mov_b64_e32 v[72:73], v[38:39]
	v_mov_b64_e32 v[70:71], v[36:37]
	v_mov_b64_e32 v[68:69], v[34:35]
	v_mov_b64_e32 v[66:67], v[32:33]
	v_mov_b64_e32 v[94:95], v[44:45]
	v_mov_b64_e32 v[92:93], v[42:43]
	v_mov_b64_e32 v[90:91], v[40:41]
	v_mov_b64_e32 v[88:89], v[38:39]
	v_mov_b64_e32 v[86:87], v[36:37]
	v_mov_b64_e32 v[84:85], v[34:35]
	v_mov_b64_e32 v[82:83], v[32:33]
	v_mov_b64_e32 v[62:63], v[44:45]
	v_mov_b64_e32 v[60:61], v[42:43]
	v_mov_b64_e32 v[58:59], v[40:41]
	v_mov_b64_e32 v[56:57], v[38:39]
	v_mov_b64_e32 v[54:55], v[36:37]
	v_mov_b64_e32 v[52:53], v[34:35]
	v_mov_b64_e32 v[50:51], v[32:33]
	v_mov_b64_e32 v[48:49], v[46:47]
	v_cvt_pk_bf16_f32 v202, v2, v3
	v_cvt_pk_bf16_f32 v201, v4, v5
	v_cvt_pk_bf16_f32 v200, v6, v7
	v_cvt_pk_bf16_f32 v199, v8, v9
	v_cvt_pk_bf16_f32 v198, v10, v11
	v_cvt_pk_bf16_f32 v197, v12, v13
	v_cvt_pk_bf16_f32 v196, v14, v15
	v_cvt_pk_bf16_f32 v195, v16, v17
	v_cvt_pk_bf16_f32 v194, v18, v19
	v_cvt_pk_bf16_f32 v193, v20, v21
	v_cvt_pk_bf16_f32 v192, v22, v23
	v_cvt_pk_bf16_f32 v191, v24, v25
	v_cvt_pk_bf16_f32 v190, v26, v27
	v_cvt_pk_bf16_f32 v189, v28, v29
	v_cvt_pk_bf16_f32 v188, v30, v31
	v_cvt_pk_bf16_f32 v170, v0, v1
	v_mov_b64_e32 v[46:47], v[44:45]
	v_mov_b64_e32 v[44:45], v[42:43]
	v_mov_b64_e32 v[42:43], v[40:41]
	v_mov_b64_e32 v[40:41], v[38:39]
	v_mov_b64_e32 v[38:39], v[36:37]
	v_mov_b64_e32 v[36:37], v[34:35]
	v_mov_b64_e32 v[34:35], v[32:33]
	s_branch .LBB0_1120
